# grid barrier: every workgroup polls the cross-XCD release word directly, per-XCD relay add removed (14 in-loop barriers)
# speedup vs baseline: 1.0026x; 1.0017x over previous
; __device__ __forceinline__ unsigned xb_ld(unsigned* p)              { return __hip_atomic_load(p, __ATOMIC_RELAXED, __HIP_MEMORY_SCOPE_AGENT); }
; __device__ __forceinline__ unsigned xb_add(unsigned* p, unsigned v) { return __hip_atomic_fetch_add(p, v, __ATOMIC_RELAXED, __HIP_MEMORY_SCOPE_AGENT); }
; #define XB_SPIN(cond, bar) do { unsigned _sp = 0; while (cond) { __builtin_amdgcn_s_sleep(1); \
;     if ((++_sp & 255u) == 0u) { if (xb_ld(&(bar)[XB_TMO])) break; if (_sp > XB_SPIN_CAP) { atomicAdd(&(bar)[XB_TMO], 1u); break; } } } } while (0)
; __device__ __forceinline__ void xcd_barrier(const XcdBarrier& b) {
;     ...
;         const unsigned old = xb_add(&bar[XB_XSUB(b.x)], 1u);
;         const unsigned gen = old / nloc;
;         if (old + 1u == (gen + 1u) * nloc) {
;             __builtin_amdgcn_fence(__ATOMIC_RELEASE, "agent");
;             asm volatile("s_waitcnt vmcnt(0)" ::: "memory");
;             const unsigned og = xb_add(&bar[XB_TOP], 1u);
;             const unsigned tg = og / nx;
;             if (og + 1u == (tg + 1u) * nx) xb_add(&bar[XB_TOPGEN], 1u);
;             else XB_SPIN(xb_ld(&bar[XB_TOPGEN]) == tg, bar);
;             __builtin_amdgcn_fence(__ATOMIC_ACQUIRE, "agent");
;             xb_add(&bar[XB_XGEN(b.x)], 1u);
;             asm volatile("s_waitcnt vmcnt(0)" ::: "memory");
;         } else {
;             XB_SPIN(xb_ld(&bar[XB_XGEN(b.x)]) == gen, bar);
.LBB0_194:
	s_or_b64 exec, exec, s[8:9]
	v_cvt_f32_u32_e32 v10, v8
	s_waitcnt vmcnt(0)
	v_readfirstlane_b32 s6, v9
	v_sub_u32_e32 v9, 0, v8
	v_rcp_iflag_f32_e32 v10, v10
	v_add_u32_e32 v11, s6, v7
	v_mul_f32_e32 v10, 0x4f7ffffe, v10
	v_cvt_u32_f32_e32 v10, v10
	v_mul_lo_u32 v7, v9, v10
	v_mul_hi_u32 v7, v10, v7
	v_add_u32_e32 v7, v10, v7
	v_mul_hi_u32 v7, v11, v7
	v_mul_lo_u32 v9, v7, v8
	v_sub_u32_e32 v9, v11, v9
	v_add_u32_e32 v10, 1, v7
	v_cmp_ge_u32_e32 vcc, v9, v8
	s_nop 1
	v_cndmask_b32_e32 v7, v7, v10, vcc
	v_sub_u32_e32 v10, v9, v8
	v_cndmask_b32_e32 v9, v9, v10, vcc
	v_add_u32_e32 v10, 1, v7
	v_cmp_ge_u32_e32 vcc, v9, v8
	v_add_u32_e32 v9, 1, v11
	s_nop 0
	v_cndmask_b32_e32 v7, v7, v10, vcc
	v_mul_lo_u32 v10, v8, v7
	v_add_u32_e32 v8, v10, v8
	v_cmp_ne_u32_e32 vcc, v9, v8
	s_and_saveexec_b64 s[6:7], vcc
	s_xor_b64 s[6:7], exec, s[6:7]
	s_cbranch_execz .LBB0_208
	s_waitcnt lgkmcnt(0)
	buffer_inv sc1
	s_nop 0
	s_nop 0
	global_load_dword v6, v157, s[50:51] sc1
	s_mov_b32 s10, s50
	s_mov_b32 s11, s51
	s_waitcnt vmcnt(0)
	v_cmp_eq_u32_e32 vcc, v6, v7
	s_and_saveexec_b64 s[8:9], vcc
	s_cbranch_execz .LBB0_207
	s_mov_b32 s16, 1
	s_mov_b64 s[12:13], 0
	s_branch .LBB0_198

; __device__ __forceinline__ unsigned xb_add(unsigned* p, unsigned v) { return __hip_atomic_fetch_add(p, v, __ATOMIC_RELAXED, __HIP_MEMORY_SCOPE_AGENT); }
; __device__ __forceinline__ void xcd_barrier(const XcdBarrier& b) {
;     ...
;             __builtin_amdgcn_fence(__ATOMIC_ACQUIRE, "agent");
;             xb_add(&bar[XB_XGEN(b.x)], 1u);
;             asm volatile("s_waitcnt vmcnt(0)" ::: "memory");
.LBB0_225:
	s_or_b64 exec, exec, s[6:7]
	s_mov_b64 s[6:7], exec
	v_mbcnt_lo_u32_b32 v6, s6, 0
	v_mbcnt_hi_u32_b32 v6, s7, v6
	v_cmp_eq_u32_e32 vcc, 0, v6
	s_waitcnt vmcnt(0)
	buffer_inv sc1
	s_and_saveexec_b64 s[8:9], vcc
	s_cbranch_execz .LBB0_227
	s_bcnt1_i32_b64 s6, s[6:7]
	v_mov_b32_e32 v6, s6
	v_mov_b32_e32 v7, 0x2000
	s_nop 0
	s_nop 0
	s_nop 0
